# IN GEMM non-rotary tiles: first half of the epilogue (accumulators final after phase 2) interleaved into the last iteration's phase-3 MFMA block
# speedup vs baseline: 1.0007x; 1.0007x over previous
.LBB0_140:
	s_cmp_lg_u32 s59, 28
	s_cbranch_scc1 .Lk_norm
	s_add_i32 s60, s55, -12
	s_cmp_lt_u32 s60, 6
	s_cbranch_scc0 .Lk_last

.Lk_last:
	s_add_u32 s10, s8, 0xfff80080
	s_addc_u32 s11, s9, -1
	s_add_i32 s60, 0, 0x10000
	s_cmp_eq_u32 s59, 28
	s_cselect_b32 s15, s0, s11
	s_cselect_b32 s14, s1, s10
	v_add_u32_e32 v0, s60, v167
	s_cselect_b32 s11, s25, s58
	s_cselect_b32 s10, s27, s57
	s_add_i32 s62, 0, 0x14000
	ds_read_b128 v[130:133], v0
	ds_read_b128 v[158:161], v0 offset:1024
	ds_read_b128 v[162:165], v0 offset:2048
	ds_read_b128 v[170:173], v0 offset:3072
	v_add_u32_e32 v0, s62, v167
	ds_read_b128 v[174:177], v0
	ds_read_b128 v[178:181], v0 offset:1024
	ds_read_b128 v[182:185], v0 offset:2048
	ds_read_b128 v[186:189], v0 offset:3072
	s_mov_b32 m0, s52
	s_nop 0
	global_load_lds_dwordx4 v140, s[74:75]
	s_mov_b32 m0, s53
	s_nop 0
	global_load_lds_dwordx4 v136, s[74:75]
	s_add_i32 m0, s48, 0xc000
	ds_read_b128 v[190:193], v169
	ds_read_b128 v[194:197], v169 offset:1024
	ds_read_b128 v[198:201], v169 offset:2048
	ds_read_b128 v[216:219], v169 offset:3072
	ds_read_b128 v[220:223], v169 offset:4096
	ds_read_b128 v[224:227], v169 offset:5120
	ds_read_b128 v[228:231], v169 offset:6144
	ds_read_b128 v[232:235], v169 offset:7168
	global_load_lds_dwordx4 v156, s[8:9]
	s_add_i32 m0, s48, 0xe000
	s_nop 0
	global_load_lds_dwordx4 v146, s[8:9]
	s_waitcnt vmcnt(8)
	s_waitcnt lgkmcnt(0)
	s_barrier
	s_setprio 1
	s_waitcnt lgkmcnt(0)
	v_mfma_f32_16x16x32_bf16 v[126:129], v[130:133], v[190:193], v[126:129]
	v_mfma_f32_16x16x32_bf16 v[122:125], v[162:165], v[190:193], v[122:125]
	v_mfma_f32_16x16x32_bf16 v[110:113], v[130:133], v[198:201], v[110:113]
	v_mfma_f32_16x16x32_bf16 v[106:109], v[162:165], v[198:201], v[106:109]
	v_mfma_f32_16x16x32_bf16 v[94:97], v[130:133], v[220:223], v[94:97]
	v_mfma_f32_16x16x32_bf16 v[90:93], v[162:165], v[220:223], v[90:93]
	v_mfma_f32_16x16x32_bf16 v[78:81], v[130:133], v[228:231], v[78:81]
	v_mfma_f32_16x16x32_bf16 v[74:77], v[162:165], v[228:231], v[74:77]
	v_mfma_f32_16x16x32_bf16 v[126:129], v[158:161], v[194:197], v[126:129]
	v_mfma_f32_16x16x32_bf16 v[122:125], v[170:173], v[194:197], v[122:125]
	v_mfma_f32_16x16x32_bf16 v[110:113], v[158:161], v[216:219], v[110:113]
	v_mfma_f32_16x16x32_bf16 v[106:109], v[170:173], v[216:219], v[106:109]
	v_mfma_f32_16x16x32_bf16 v[94:97], v[158:161], v[224:227], v[94:97]
	v_mfma_f32_16x16x32_bf16 v[90:93], v[170:173], v[224:227], v[90:93]
	v_mfma_f32_16x16x32_bf16 v[78:81], v[158:161], v[232:235], v[78:81]
	v_mfma_f32_16x16x32_bf16 v[74:77], v[170:173], v[232:235], v[74:77]
	s_setprio 0
	s_setprio 1
	v_mfma_f32_16x16x32_bf16 v[118:121], v[174:177], v[190:193], v[118:121]
	v_mfma_f32_16x16x32_bf16 v[114:117], v[182:185], v[190:193], v[114:117]
	v_mfma_f32_16x16x32_bf16 v[102:105], v[174:177], v[198:201], v[102:105]
	v_mfma_f32_16x16x32_bf16 v[98:101], v[182:185], v[198:201], v[98:101]
	v_mfma_f32_16x16x32_bf16 v[86:89], v[174:177], v[220:223], v[86:89]
	v_mfma_f32_16x16x32_bf16 v[82:85], v[182:185], v[220:223], v[82:85]
	v_mfma_f32_16x16x32_bf16 v[70:73], v[174:177], v[228:231], v[70:73]
	v_mfma_f32_16x16x32_bf16 v[66:69], v[182:185], v[228:231], v[66:69]
	v_mfma_f32_16x16x32_bf16 v[118:121], v[178:181], v[194:197], v[118:121]
	v_mfma_f32_16x16x32_bf16 v[114:117], v[186:189], v[194:197], v[114:117]
	v_mfma_f32_16x16x32_bf16 v[102:105], v[178:181], v[216:219], v[102:105]
	v_mfma_f32_16x16x32_bf16 v[98:101], v[186:189], v[216:219], v[98:101]
	v_mfma_f32_16x16x32_bf16 v[86:89], v[178:181], v[224:227], v[86:89]
	v_mfma_f32_16x16x32_bf16 v[82:85], v[186:189], v[224:227], v[82:85]
	v_mfma_f32_16x16x32_bf16 v[70:73], v[178:181], v[232:235], v[70:73]
	v_mfma_f32_16x16x32_bf16 v[66:69], v[186:189], v[232:235], v[66:69]
	s_setprio 0
	s_barrier
	s_add_i32 s60, s60, s29
	s_add_u32 s72, s10, s44
	s_addc_u32 s73, s11, s45
	s_mov_b32 m0, s60
	ds_read_b128 v[190:193], v169 offset:16384
	ds_read_b128 v[194:197], v169 offset:17408
	ds_read_b128 v[198:201], v169 offset:18432
	ds_read_b128 v[216:219], v169 offset:19456
	ds_read_b128 v[220:223], v169 offset:20480
	ds_read_b128 v[224:227], v169 offset:21504
	ds_read_b128 v[228:231], v169 offset:22528
	ds_read_b128 v[232:235], v169 offset:23552
	global_load_lds_dwordx4 v138, s[10:11]
	s_add_i32 m0, s60, 0x2000
	s_add_u32 s60, s10, 0x80000
	s_addc_u32 s61, s11, 0
	s_add_i32 s62, s62, s29
	global_load_lds_dwordx4 v134, s[10:11]
	s_mov_b32 m0, s62
	s_add_u32 s74, s14, s44
	s_addc_u32 s75, s15, s45
	global_load_lds_dwordx4 v138, s[60:61]
	s_add_i32 m0, s62, 0x2000
	s_nop 0
	global_load_lds_dwordx4 v134, s[60:61]
	s_waitcnt vmcnt(6)
	s_waitcnt lgkmcnt(0)
	s_barrier
	s_setprio 1
	s_waitcnt lgkmcnt(0)
	v_mfma_f32_16x16x32_bf16 v[62:65], v[130:133], v[190:193], v[62:65]
	v_mfma_f32_16x16x32_bf16 v[58:61], v[162:165], v[190:193], v[58:61]
	v_mfma_f32_16x16x32_bf16 v[46:49], v[130:133], v[198:201], v[46:49]
	v_mfma_f32_16x16x32_bf16 v[42:45], v[162:165], v[198:201], v[42:45]
	v_mfma_f32_16x16x32_bf16 v[30:33], v[130:133], v[220:223], v[30:33]
	v_mfma_f32_16x16x32_bf16 v[26:29], v[162:165], v[220:223], v[26:29]
	v_mfma_f32_16x16x32_bf16 v[14:17], v[130:133], v[228:231], v[14:17]
	v_mfma_f32_16x16x32_bf16 v[10:13], v[162:165], v[228:231], v[10:13]
	v_mfma_f32_16x16x32_bf16 v[62:65], v[158:161], v[194:197], v[62:65]
	v_mfma_f32_16x16x32_bf16 v[58:61], v[170:173], v[194:197], v[58:61]
	v_mfma_f32_16x16x32_bf16 v[46:49], v[158:161], v[216:219], v[46:49]
	v_mfma_f32_16x16x32_bf16 v[42:45], v[170:173], v[216:219], v[42:45]
	v_mfma_f32_16x16x32_bf16 v[30:33], v[158:161], v[224:227], v[30:33]
	v_mfma_f32_16x16x32_bf16 v[26:29], v[170:173], v[224:227], v[26:29]
	v_mfma_f32_16x16x32_bf16 v[14:17], v[158:161], v[232:235], v[14:17]
	v_mfma_f32_16x16x32_bf16 v[10:13], v[170:173], v[232:235], v[10:13]
	s_setprio 0
	s_setprio 1
	v_mfma_f32_16x16x32_bf16 v[54:57], v[174:177], v[190:193], v[54:57]
	v_mfma_f32_16x16x32_bf16 v[50:53], v[182:185], v[190:193], v[50:53]
	v_mfma_f32_16x16x32_bf16 v[38:41], v[174:177], v[198:201], v[38:41]
	v_mfma_f32_16x16x32_bf16 v[34:37], v[182:185], v[198:201], v[34:37]
	v_mfma_f32_16x16x32_bf16 v[22:25], v[174:177], v[220:223], v[22:25]
	v_mfma_f32_16x16x32_bf16 v[18:21], v[182:185], v[220:223], v[18:21]
	v_mfma_f32_16x16x32_bf16 v[6:9], v[174:177], v[228:231], v[6:9]
	v_mfma_f32_16x16x32_bf16 v[2:5], v[182:185], v[228:231], v[2:5]
	v_mfma_f32_16x16x32_bf16 v[54:57], v[178:181], v[194:197], v[54:57]
	v_mfma_f32_16x16x32_bf16 v[50:53], v[186:189], v[194:197], v[50:53]
	v_mfma_f32_16x16x32_bf16 v[38:41], v[178:181], v[216:219], v[38:41]
	v_mfma_f32_16x16x32_bf16 v[34:37], v[186:189], v[216:219], v[34:37]
	v_mfma_f32_16x16x32_bf16 v[22:25], v[178:181], v[224:227], v[22:25]
	v_mfma_f32_16x16x32_bf16 v[18:21], v[186:189], v[224:227], v[18:21]
	v_mfma_f32_16x16x32_bf16 v[6:9], v[178:181], v[232:235], v[6:9]
	v_mfma_f32_16x16x32_bf16 v[2:5], v[186:189], v[232:235], v[2:5]
	s_setprio 0
	s_barrier
	s_add_i32 s60, 0, 0x18000
	v_add_u32_e32 v0, s60, v167
	s_add_i32 s61, 0, 0x1c000
	ds_read_b128 v[130:133], v0
	ds_read_b128 v[158:161], v0 offset:1024
	ds_read_b128 v[162:165], v0 offset:2048
	ds_read_b128 v[170:173], v0 offset:3072
	v_add_u32_e32 v0, s61, v167
	ds_read_b128 v[174:177], v0
	ds_read_b128 v[178:181], v0 offset:1024
	ds_read_b128 v[182:185], v0 offset:2048
	ds_read_b128 v[186:189], v0 offset:3072
	s_mov_b32 m0, s48
	s_nop 0
	global_load_lds_dwordx4 v140, s[14:15]
	s_mov_b32 m0, s49
	s_nop 0
	global_load_lds_dwordx4 v136, s[14:15]
	s_add_u32 s14, s14, 0x80000
	s_addc_u32 s15, s15, 0
	s_mov_b32 m0, s50
	ds_read_b128 v[190:193], v169 offset:32768
	ds_read_b128 v[194:197], v169 offset:33792
	ds_read_b128 v[198:201], v169 offset:34816
	ds_read_b128 v[216:219], v169 offset:35840
	ds_read_b128 v[220:223], v169 offset:36864
	ds_read_b128 v[224:227], v169 offset:37888
	ds_read_b128 v[228:231], v169 offset:38912
	ds_read_b128 v[232:235], v169 offset:39936
	global_load_lds_dwordx4 v140, s[14:15]
	s_mov_b32 m0, s51
	s_nop 0
	global_load_lds_dwordx4 v136, s[14:15]
	s_waitcnt vmcnt(8)
	s_waitcnt lgkmcnt(0)
	s_barrier
	s_setprio 1
	s_waitcnt lgkmcnt(0)
	v_mfma_f32_16x16x32_bf16 v[126:129], v[130:133], v[190:193], v[126:129]
	v_mfma_f32_16x16x32_bf16 v[122:125], v[162:165], v[190:193], v[122:125]
	v_mfma_f32_16x16x32_bf16 v[110:113], v[130:133], v[198:201], v[110:113]
	v_mfma_f32_16x16x32_bf16 v[106:109], v[162:165], v[198:201], v[106:109]
	v_mfma_f32_16x16x32_bf16 v[94:97], v[130:133], v[220:223], v[94:97]
	v_mfma_f32_16x16x32_bf16 v[90:93], v[162:165], v[220:223], v[90:93]
	v_mfma_f32_16x16x32_bf16 v[78:81], v[130:133], v[228:231], v[78:81]
	v_mfma_f32_16x16x32_bf16 v[74:77], v[162:165], v[228:231], v[74:77]
	v_mfma_f32_16x16x32_bf16 v[126:129], v[158:161], v[194:197], v[126:129]
	v_mfma_f32_16x16x32_bf16 v[122:125], v[170:173], v[194:197], v[122:125]
	v_mfma_f32_16x16x32_bf16 v[110:113], v[158:161], v[216:219], v[110:113]
	v_mfma_f32_16x16x32_bf16 v[106:109], v[170:173], v[216:219], v[106:109]
	v_mfma_f32_16x16x32_bf16 v[94:97], v[158:161], v[224:227], v[94:97]
	v_mfma_f32_16x16x32_bf16 v[90:93], v[170:173], v[224:227], v[90:93]
	v_mfma_f32_16x16x32_bf16 v[78:81], v[158:161], v[232:235], v[78:81]
	v_mfma_f32_16x16x32_bf16 v[74:77], v[170:173], v[232:235], v[74:77]
	s_setprio 0
	s_setprio 1
	v_mfma_f32_16x16x32_bf16 v[118:121], v[174:177], v[190:193], v[118:121]
	v_mfma_f32_16x16x32_bf16 v[114:117], v[182:185], v[190:193], v[114:117]
	v_mfma_f32_16x16x32_bf16 v[102:105], v[174:177], v[198:201], v[102:105]
	v_mfma_f32_16x16x32_bf16 v[98:101], v[182:185], v[198:201], v[98:101]
	v_mfma_f32_16x16x32_bf16 v[86:89], v[174:177], v[220:223], v[86:89]
	v_mfma_f32_16x16x32_bf16 v[82:85], v[182:185], v[220:223], v[82:85]
	v_mfma_f32_16x16x32_bf16 v[70:73], v[174:177], v[228:231], v[70:73]
	v_mfma_f32_16x16x32_bf16 v[66:69], v[182:185], v[228:231], v[66:69]
	v_mfma_f32_16x16x32_bf16 v[118:121], v[178:181], v[194:197], v[118:121]
	v_mfma_f32_16x16x32_bf16 v[114:117], v[186:189], v[194:197], v[114:117]
	v_mfma_f32_16x16x32_bf16 v[102:105], v[178:181], v[216:219], v[102:105]
	v_mfma_f32_16x16x32_bf16 v[98:101], v[186:189], v[216:219], v[98:101]
	v_mfma_f32_16x16x32_bf16 v[86:89], v[178:181], v[224:227], v[86:89]
	v_mfma_f32_16x16x32_bf16 v[82:85], v[186:189], v[224:227], v[82:85]
	v_mfma_f32_16x16x32_bf16 v[70:73], v[178:181], v[232:235], v[70:73]
	v_mfma_f32_16x16x32_bf16 v[66:69], v[186:189], v[232:235], v[66:69]
	s_setprio 0
	s_barrier
	s_add_i32 s14, s60, s29
	s_mov_b32 m0, s14
	ds_read_b128 v[190:193], v169 offset:49152
	ds_read_b128 v[194:197], v169 offset:50176
	ds_read_b128 v[198:201], v169 offset:51200
	ds_read_b128 v[216:219], v169 offset:52224
	ds_read_b128 v[220:223], v169 offset:53248
	ds_read_b128 v[224:227], v169 offset:54272
	ds_read_b128 v[228:231], v169 offset:55296
	ds_read_b128 v[232:235], v169 offset:56320
	global_load_lds_dwordx4 v138, s[72:73]
	s_add_i32 m0, s14, 0x2000
	s_add_u32 s10, s10, 0x80080
	s_addc_u32 s11, s11, 0
	s_add_i32 s14, s61, s29
	global_load_lds_dwordx4 v134, s[72:73]
	s_mov_b32 m0, s14
	s_nop 0
	global_load_lds_dwordx4 v138, s[10:11]
	s_add_i32 m0, s14, 0x2000
	s_nop 0
	global_load_lds_dwordx4 v134, s[10:11]
	s_waitcnt vmcnt(6)
	s_waitcnt lgkmcnt(0)
	s_barrier
	s_setprio 1
	s_waitcnt lgkmcnt(0)
	v_mfma_f32_16x16x32_bf16 v[62:65], v[130:133], v[190:193], v[62:65]
	v_lshl_add_u32 v238, s56, 8, v166
	v_lshl_or_b32 v236, s55, 8, v168
	v_mfma_f32_16x16x32_bf16 v[58:61], v[162:165], v[190:193], v[58:61]
	v_ashrrev_i32_e32 v237, 31, v236
	v_mov_b64_e32 v[240:241], s[12:13]
	v_mfma_f32_16x16x32_bf16 v[46:49], v[130:133], v[198:201], v[46:49]
	v_mad_i64_i32 v[240:241], vcc, v238, s43, v[240:241]
	v_cvt_pk_bf16_f32 v126, v126, v127
	v_mfma_f32_16x16x32_bf16 v[42:45], v[162:165], v[198:201], v[42:45]
	v_cvt_pk_bf16_f32 v127, v128, v129
	v_cvt_pk_bf16_f32 v128, v122, v123
	v_mfma_f32_16x16x32_bf16 v[30:33], v[130:133], v[220:223], v[30:33]
	v_cvt_pk_bf16_f32 v129, v124, v125
	v_lshl_add_u64 v[240:241], v[236:237], 1, v[240:241]
	v_mfma_f32_16x16x32_bf16 v[26:29], v[162:165], v[220:223], v[26:29]
	v_cvt_pk_bf16_f32 v118, v118, v119
	v_cvt_pk_bf16_f32 v119, v120, v121
	v_mfma_f32_16x16x32_bf16 v[14:17], v[130:133], v[228:231], v[14:17]
	v_cvt_pk_bf16_f32 v120, v114, v115
	v_cvt_pk_bf16_f32 v121, v116, v117
	v_mfma_f32_16x16x32_bf16 v[10:13], v[162:165], v[228:231], v[10:13]
	global_store_dwordx4 v[240:241], v[126:129], off sc1 nt
	global_store_dwordx4 v[240:241], v[118:121], off offset:256 sc1 nt
	v_mfma_f32_16x16x32_bf16 v[62:65], v[158:161], v[194:197], v[62:65]
	v_add_u32_e32 v239, 16, v238
	v_mov_b64_e32 v[240:241], s[12:13]
	v_mfma_f32_16x16x32_bf16 v[58:61], v[170:173], v[194:197], v[58:61]
	v_mad_i64_i32 v[240:241], vcc, v239, s43, v[240:241]
	v_cvt_pk_bf16_f32 v110, v110, v111
	v_mfma_f32_16x16x32_bf16 v[46:49], v[158:161], v[216:219], v[46:49]
	v_cvt_pk_bf16_f32 v111, v112, v113
	v_cvt_pk_bf16_f32 v112, v106, v107
	v_mfma_f32_16x16x32_bf16 v[42:45], v[170:173], v[216:219], v[42:45]
	v_cvt_pk_bf16_f32 v113, v108, v109
	v_lshl_add_u64 v[240:241], v[236:237], 1, v[240:241]
	v_mfma_f32_16x16x32_bf16 v[30:33], v[158:161], v[224:227], v[30:33]
	v_cvt_pk_bf16_f32 v102, v102, v103
	v_cvt_pk_bf16_f32 v103, v104, v105
	v_mfma_f32_16x16x32_bf16 v[26:29], v[170:173], v[224:227], v[26:29]
	v_cvt_pk_bf16_f32 v104, v98, v99
	v_cvt_pk_bf16_f32 v105, v100, v101
	v_mfma_f32_16x16x32_bf16 v[14:17], v[158:161], v[232:235], v[14:17]
	global_store_dwordx4 v[240:241], v[110:113], off sc1 nt
	global_store_dwordx4 v[240:241], v[102:105], off offset:256 sc1 nt
	v_mfma_f32_16x16x32_bf16 v[10:13], v[170:173], v[232:235], v[10:13]
	v_add_u32_e32 v239, 32, v238
	v_mov_b64_e32 v[240:241], s[12:13]
	s_setprio 0
	s_setprio 1
	v_mfma_f32_16x16x32_bf16 v[54:57], v[174:177], v[190:193], v[54:57]
	v_mad_i64_i32 v[240:241], vcc, v239, s43, v[240:241]
	v_cvt_pk_bf16_f32 v94, v94, v95
	v_mfma_f32_16x16x32_bf16 v[50:53], v[182:185], v[190:193], v[50:53]
	v_cvt_pk_bf16_f32 v95, v96, v97
	v_cvt_pk_bf16_f32 v96, v90, v91
	v_mfma_f32_16x16x32_bf16 v[38:41], v[174:177], v[198:201], v[38:41]
	v_cvt_pk_bf16_f32 v97, v92, v93
	v_lshl_add_u64 v[240:241], v[236:237], 1, v[240:241]
	v_mfma_f32_16x16x32_bf16 v[34:37], v[182:185], v[198:201], v[34:37]
	v_cvt_pk_bf16_f32 v86, v86, v87
	v_cvt_pk_bf16_f32 v87, v88, v89
	v_mfma_f32_16x16x32_bf16 v[22:25], v[174:177], v[220:223], v[22:25]
	v_cvt_pk_bf16_f32 v88, v82, v83
	v_cvt_pk_bf16_f32 v89, v84, v85
	v_mfma_f32_16x16x32_bf16 v[18:21], v[182:185], v[220:223], v[18:21]
	global_store_dwordx4 v[240:241], v[94:97], off sc1 nt
	global_store_dwordx4 v[240:241], v[86:89], off offset:256 sc1 nt
	v_mfma_f32_16x16x32_bf16 v[6:9], v[174:177], v[228:231], v[6:9]
	v_add_u32_e32 v239, 48, v238
	v_mov_b64_e32 v[240:241], s[12:13]
	v_mfma_f32_16x16x32_bf16 v[2:5], v[182:185], v[228:231], v[2:5]
	v_mad_i64_i32 v[240:241], vcc, v239, s43, v[240:241]
	v_cvt_pk_bf16_f32 v78, v78, v79
	v_mfma_f32_16x16x32_bf16 v[54:57], v[178:181], v[194:197], v[54:57]
	v_cvt_pk_bf16_f32 v79, v80, v81
	v_cvt_pk_bf16_f32 v80, v74, v75
	v_mfma_f32_16x16x32_bf16 v[50:53], v[186:189], v[194:197], v[50:53]
	v_cvt_pk_bf16_f32 v81, v76, v77
	v_lshl_add_u64 v[240:241], v[236:237], 1, v[240:241]
	v_mfma_f32_16x16x32_bf16 v[38:41], v[178:181], v[216:219], v[38:41]
	v_cvt_pk_bf16_f32 v70, v70, v71
	v_cvt_pk_bf16_f32 v71, v72, v73
	v_mfma_f32_16x16x32_bf16 v[34:37], v[186:189], v[216:219], v[34:37]
	v_cvt_pk_bf16_f32 v72, v66, v67
	v_cvt_pk_bf16_f32 v73, v68, v69
	v_mfma_f32_16x16x32_bf16 v[22:25], v[178:181], v[224:227], v[22:25]
	global_store_dwordx4 v[240:241], v[78:81], off sc1 nt
	global_store_dwordx4 v[240:241], v[70:73], off offset:256 sc1 nt
	v_mfma_f32_16x16x32_bf16 v[18:21], v[186:189], v[224:227], v[18:21]
	v_mfma_f32_16x16x32_bf16 v[6:9], v[178:181], v[232:235], v[6:9]
	v_mfma_f32_16x16x32_bf16 v[2:5], v[186:189], v[232:235], v[2:5]
	s_setprio 0
	s_barrier
	s_add_i32 s59, s59, 2
	s_add_u32 s57, s57, 0x100
	s_addc_u32 s58, s58, 0
	s_add_u32 s8, s8, 0x100
	s_addc_u32 s9, s9, 0
	s_cmp_gt_u32 s59, 29
.Lepi_last_entry:
	v_lshl_add_u32 v170, s56, 8, v166
	v_lshl_or_b32 v158, s55, 8, v168
	v_ashrrev_i32_e32 v159, 31, v158
	s_branch .Lepi_fast_b

.Lepi_fast_b:
	v_add_u32_e32 v174, 0x80, v170
	v_mov_b64_e32 v[172:173], s[12:13]
	v_mad_i64_i32 v[172:173], s[0:1], v174, s43, v[172:173]
	v_cvt_pk_bf16_f32 v62, v62, v63
	v_cvt_pk_bf16_f32 v63, v64, v65
	v_cvt_pk_bf16_f32 v64, v58, v59
	v_cvt_pk_bf16_f32 v65, v60, v61
	v_lshl_add_u64 v[172:173], v[158:159], 1, v[172:173]
	v_cvt_pk_bf16_f32 v54, v54, v55
	v_cvt_pk_bf16_f32 v55, v56, v57
	v_cvt_pk_bf16_f32 v56, v50, v51
	v_cvt_pk_bf16_f32 v57, v52, v53
	global_store_dwordx4 v[172:173], v[62:65], off sc1 nt
	global_store_dwordx4 v[172:173], v[54:57], off offset:256 sc1 nt
	v_add_u32_e32 v174, 0x90, v170
	v_mov_b64_e32 v[172:173], s[12:13]
	v_mad_i64_i32 v[172:173], s[0:1], v174, s43, v[172:173]
	v_cvt_pk_bf16_f32 v46, v46, v47
	v_cvt_pk_bf16_f32 v47, v48, v49
	v_cvt_pk_bf16_f32 v48, v42, v43
	v_cvt_pk_bf16_f32 v49, v44, v45
	v_lshl_add_u64 v[172:173], v[158:159], 1, v[172:173]
	v_cvt_pk_bf16_f32 v38, v38, v39
	v_cvt_pk_bf16_f32 v39, v40, v41
	v_cvt_pk_bf16_f32 v40, v34, v35
	v_cvt_pk_bf16_f32 v41, v36, v37
	global_store_dwordx4 v[172:173], v[46:49], off sc1 nt
	global_store_dwordx4 v[172:173], v[38:41], off offset:256 sc1 nt
	v_add_u32_e32 v174, 0xa0, v170
	v_mov_b64_e32 v[172:173], s[12:13]
	v_mad_i64_i32 v[172:173], s[0:1], v174, s43, v[172:173]
	v_cvt_pk_bf16_f32 v30, v30, v31
	v_cvt_pk_bf16_f32 v31, v32, v33
	v_cvt_pk_bf16_f32 v32, v26, v27
	v_cvt_pk_bf16_f32 v33, v28, v29
	v_lshl_add_u64 v[172:173], v[158:159], 1, v[172:173]
	v_cvt_pk_bf16_f32 v22, v22, v23
	v_cvt_pk_bf16_f32 v23, v24, v25
	v_cvt_pk_bf16_f32 v24, v18, v19
	v_cvt_pk_bf16_f32 v25, v20, v21
	global_store_dwordx4 v[172:173], v[30:33], off sc1 nt
	global_store_dwordx4 v[172:173], v[22:25], off offset:256 sc1 nt
	v_add_u32_e32 v174, 0xb0, v170
	v_mov_b64_e32 v[172:173], s[12:13]
	v_mad_i64_i32 v[172:173], s[0:1], v174, s43, v[172:173]
	v_cvt_pk_bf16_f32 v14, v14, v15
	v_cvt_pk_bf16_f32 v15, v16, v17
	v_cvt_pk_bf16_f32 v16, v10, v11
	v_cvt_pk_bf16_f32 v17, v12, v13
	v_lshl_add_u64 v[172:173], v[158:159], 1, v[172:173]
	v_cvt_pk_bf16_f32 v6, v6, v7
	v_cvt_pk_bf16_f32 v7, v8, v9
	v_cvt_pk_bf16_f32 v8, v2, v3
	v_cvt_pk_bf16_f32 v9, v4, v5
	global_store_dwordx4 v[172:173], v[14:17], off sc1 nt
	global_store_dwordx4 v[172:173], v[6:9], off offset:256 sc1 nt
	s_nop 1
	s_branch .Lepi_join
